# resid gemm80: tile->block map so that the two blocks sharing a CU use the same weight tile (L1 reuse)
# baseline (speedup 1.0000x reference)
.LBB0_261:
	s_and_b32 s26, s70, 0xff
	s_and_b32 s28, s26, 31
	s_lshr_b32 s38, s70, 8
	s_lshl_b32 s38, s38, 5
	s_add_i32 s28, s28, s38
	s_lshr_b32 s26, s26, 5
	s_lshl_b32 s26, s26, 6
	s_mul_i32 s54, s28, 0x50
	s_ashr_i32 s55, s54, 31
	v_mov_b32_e32 v1, v208
	s_lshl_b64 s[38:39], s[54:55], s64
	s_lshl_b64 s[38:39], s[38:39], 1
	v_ashrrev_i32_e32 v0, 6, v1
	v_bfe_u32 v4, v1, 3, 3
	v_lshl_or_b32 v4, v0, 3, v4
	s_add_u32 s38, s24, s38
	v_lshrrev_b32_e32 v2, 3, v1
	v_ashrrev_i32_e32 v5, 31, v4
	s_addc_u32 s39, s25, s39
	v_bitop3_b32 v3, v2, v1, 7 bitop3:0x28
	v_lshlrev_b64 v[4:5], s64, v[4:5]
	v_lshl_add_u64 v[4:5], v[4:5], 1, s[38:39]
	v_lshlrev_b32_e32 v128, 4, v3
	v_lshlrev_b32_e32 v42, 10, v0
	v_lshl_add_u64 v[40:41], v[4:5], 0, v[128:129]
	v_readfirstlane_b32 s28, v42
	v_add_u32_e32 v4, 0x1000, v42
	s_waitcnt lgkmcnt(0)
	s_barrier
	s_mov_b32 m0, s28
	v_readfirstlane_b32 s28, v4
	global_load_lds_dwordx4 v[40:41], off
	v_lshl_add_u64 v[44:45], v[40:41], 0, s[44:45]
	s_mov_b32 m0, s28
	v_cmp_gt_i32_e64 s[38:39], 2, v0
	global_load_lds_dwordx4 v[44:45], off
	v_lshl_add_u64 v[46:47], v[44:45], 0, s[44:45]
	s_and_saveexec_b64 s[40:41], s[38:39]
	s_cbranch_execz .LBB0_263
	v_add_u32_e32 v4, 0x2000, v42
	s_nop 0
	v_readfirstlane_b32 s28, v4
	s_mov_b32 m0, s28
	s_nop 0
	global_load_lds_dwordx4 v[46:47], off
